# GEMM epilogues: denormal scaling around v_rsq_f32 removed at 11 more sites (24 of 40)
# baseline (speedup 1.0000x reference)
.LBB0_111:
	s_or_b64 exec, exec, s[0:1]
	v_ffbh_u32_e32 v0, v137
	v_min_u32_e32 v0, 32, v0
	v_lshlrev_b64 v[124:125], v0, v[136:137]
	v_min_u32_e32 v124, 1, v124
	v_or_b32_e32 v124, v125, v124
	v_cvt_f32_u32_e32 v124, v124
	v_sub_u32_e32 v0, 32, v0
	v_ldexp_f32 v0, v124, v0
	v_mul_f32_e32 v0, 0x33800000, v0
	v_fmamk_f32 v0, v0, 0x3a800000, v210
	s_nop 1
	v_rsq_f32_e32 v0, v0
	s_nop 0
	s_nop 0
	v_pk_mul_f32 v[174:175], v[120:121], v[0:1] op_sel_hi:[1,0]
	v_pk_mul_f32 v[176:177], v[118:119], v[0:1] op_sel_hi:[1,0]
	v_pk_mul_f32 v[152:153], v[116:117], v[0:1] op_sel_hi:[1,0]
	v_pk_mul_f32 v[154:155], v[114:115], v[0:1] op_sel_hi:[1,0]
	v_cmp_lt_u32_e32 vcc, 13, v183
	s_and_saveexec_b64 s[0:1], vcc
	s_cbranch_execz .LBB0_113
	v_add_u32_e32 v0, -12, v183
	s_movk_i32 s5, 0x2c00
	v_cvt_pk_bf16_f32 v114, v176, v177
	v_cvt_pk_bf16_f32 v115, v174, v175
	v_mad_u64_u32 v[118:119], s[28:29], v0, s5, v[122:123]
	v_cvt_pk_bf16_f32 v116, v154, v155
	v_cvt_pk_bf16_f32 v117, v152, v153
	global_store_dwordx2 v[118:119], v[114:115], off
	global_store_dwordx2 v[118:119], v[116:117], off offset:256

.LBB0_117:
	s_or_b64 exec, exec, s[0:1]
	s_waitcnt vmcnt(0)
	v_ffbh_u32_e32 v0, v105
	v_min_u32_e32 v0, 32, v0
	v_lshlrev_b64 v[92:93], v0, v[104:105]
	v_min_u32_e32 v92, 1, v92
	v_or_b32_e32 v92, v93, v92
	v_cvt_f32_u32_e32 v92, v92
	v_sub_u32_e32 v0, 32, v0
	v_ldexp_f32 v0, v92, v0
	v_mul_f32_e32 v0, 0x33800000, v0
	v_fmamk_f32 v0, v0, 0x3a800000, v210
	s_nop 1
	v_rsq_f32_e32 v0, v0
	s_nop 0
	s_nop 0
	v_pk_mul_f32 v[120:121], v[88:89], v[0:1] op_sel_hi:[1,0]
	v_pk_mul_f32 v[122:123], v[86:87], v[0:1] op_sel_hi:[1,0]
	v_pk_mul_f32 v[108:109], v[84:85], v[0:1] op_sel_hi:[1,0]
	v_pk_mul_f32 v[110:111], v[82:83], v[0:1] op_sel_hi:[1,0]
	v_cmp_lt_u32_e32 vcc, 13, v129
	s_and_saveexec_b64 s[0:1], vcc
	s_cbranch_execz .LBB0_119
	v_add_u32_e32 v0, -12, v129
	s_movk_i32 s6, 0x2c00
	v_cvt_pk_bf16_f32 v82, v122, v123
	v_cvt_pk_bf16_f32 v83, v120, v121
	v_mad_u64_u32 v[86:87], s[6:7], v0, s6, v[90:91]
	v_cvt_pk_bf16_f32 v84, v110, v111
	v_cvt_pk_bf16_f32 v85, v108, v109
	global_store_dwordx2 v[86:87], v[82:83], off
	global_store_dwordx2 v[86:87], v[84:85], off offset:256

.LBB0_123:
	s_or_b64 exec, exec, s[0:1]
	s_waitcnt vmcnt(0)
	v_ffbh_u32_e32 v0, v73
	v_min_u32_e32 v0, 32, v0
	v_lshlrev_b64 v[60:61], v0, v[72:73]
	v_min_u32_e32 v60, 1, v60
	v_or_b32_e32 v60, v61, v60
	v_cvt_f32_u32_e32 v60, v60
	v_sub_u32_e32 v0, 32, v0
	v_ldexp_f32 v0, v60, v0
	v_mul_f32_e32 v0, 0x33800000, v0
	v_fmamk_f32 v0, v0, 0x3a800000, v210
	s_nop 1
	v_rsq_f32_e32 v0, v0
	s_nop 0
	s_nop 0
	v_pk_mul_f32 v[80:81], v[56:57], v[0:1] op_sel_hi:[1,0]
	v_pk_mul_f32 v[82:83], v[54:55], v[0:1] op_sel_hi:[1,0]
	v_pk_mul_f32 v[76:77], v[52:53], v[0:1] op_sel_hi:[1,0]
	v_pk_mul_f32 v[78:79], v[50:51], v[0:1] op_sel_hi:[1,0]
	v_cmp_lt_u32_e32 vcc, 13, v97
	s_and_saveexec_b64 s[0:1], vcc
	s_cbranch_execz .LBB0_125
	v_add_u32_e32 v0, -12, v97
	s_movk_i32 s6, 0x2c00
	v_cvt_pk_bf16_f32 v50, v82, v83
	v_cvt_pk_bf16_f32 v51, v80, v81
	v_mad_u64_u32 v[54:55], s[6:7], v0, s6, v[58:59]
	v_cvt_pk_bf16_f32 v52, v78, v79
	v_cvt_pk_bf16_f32 v53, v76, v77
	global_store_dwordx2 v[54:55], v[50:51], off offset:8
	global_store_dwordx2 v[54:55], v[52:53], off offset:264

.LBB0_129:
	s_or_b64 exec, exec, s[0:1]
	s_waitcnt vmcnt(0)
	v_ffbh_u32_e32 v0, v41
	v_min_u32_e32 v0, 32, v0
	v_lshlrev_b64 v[28:29], v0, v[40:41]
	v_min_u32_e32 v28, 1, v28
	v_or_b32_e32 v28, v29, v28
	v_cvt_f32_u32_e32 v28, v28
	v_sub_u32_e32 v0, 32, v0
	v_ldexp_f32 v0, v28, v0
	v_mul_f32_e32 v0, 0x33800000, v0
	v_fmamk_f32 v0, v0, 0x3a800000, v210
	s_nop 1
	v_rsq_f32_e32 v0, v0
	s_nop 0
	s_nop 0
	v_pk_mul_f32 v[68:69], v[24:25], v[0:1] op_sel_hi:[1,0]
	v_pk_mul_f32 v[64:65], v[22:23], v[0:1] op_sel_hi:[1,0]
	v_pk_mul_f32 v[48:49], v[16:17], v[0:1] op_sel_hi:[1,0]
	v_pk_mul_f32 v[50:51], v[14:15], v[0:1] op_sel_hi:[1,0]
	v_cmp_lt_u32_e32 vcc, 13, v108
	s_and_saveexec_b64 s[0:1], vcc
	s_cbranch_execz .LBB0_131
	v_add_u32_e32 v0, -12, v108
	s_movk_i32 s4, 0x2c00
	v_cvt_pk_bf16_f32 v14, v64, v65
	v_cvt_pk_bf16_f32 v15, v68, v69
	v_mad_u64_u32 v[22:23], s[6:7], v0, s4, v[26:27]
	v_cvt_pk_bf16_f32 v16, v50, v51
	v_cvt_pk_bf16_f32 v17, v48, v49
	global_store_dwordx2 v[22:23], v[14:15], off offset:8
	global_store_dwordx2 v[22:23], v[16:17], off offset:264

.LBB0_709:
	v_ffbh_u32_e32 v114, v157
	v_min_u32_e32 v116, 32, v114
	v_lshlrev_b64 v[114:115], v116, v[156:157]
	v_min_u32_e32 v114, 1, v114
	v_or_b32_e32 v114, v115, v114
	v_cvt_f32_u32_e32 v114, v114
	v_sub_u32_e32 v115, 32, v116
	v_or_b32_e32 v118, 16, v142
	s_mov_b64 s[0:1], -1
	v_ldexp_f32 v114, v114, v115
	v_mul_f32_e32 v114, 0x33800000, v114
	v_fmamk_f32 v114, v114, 0x3a800000, v210
	s_nop 1
	v_rsq_f32_e32 v114, v114
	s_nop 0
	s_nop 0
	v_pk_mul_f32 v[112:113], v[112:113], v[114:115] op_sel_hi:[1,0]
	v_pk_mul_f32 v[116:117], v[110:111], v[114:115] op_sel_hi:[1,0]
	v_pk_mul_f32 v[108:109], v[108:109], v[114:115] op_sel_hi:[1,0]
	v_pk_mul_f32 v[110:111], v[106:107], v[114:115] op_sel_hi:[1,0]
	s_and_b64 vcc, exec, s[42:43]
	s_cbranch_vccnz .LBB0_711
	v_mul_f32_e32 v106, 0xbfb8aa3b, v116
	v_exp_f32_e32 v106, v106
	v_mul_f32_e32 v115, 0xbfb8aa3b, v117
	v_exp_f32_e32 v115, v115
	v_mul_f32_e32 v107, 0xbfb8aa3b, v110
	v_exp_f32_e32 v107, v107
	v_mul_f32_e32 v119, 0xbfb8aa3b, v111
	v_add_f32_e32 v106, 1.0, v106
	v_exp_f32_e32 v119, v119
	v_rcp_f32_e32 v106, v106
	v_add_f32_e32 v115, 1.0, v115
	v_rcp_f32_e32 v115, v115
	v_add_f32_e32 v107, 1.0, v107
	v_rcp_f32_e32 v107, v107
	v_add_f32_e32 v119, 1.0, v119
	v_mul_f32_e32 v106, 0x437f0000, v106
	v_rcp_f32_e32 v119, v119
	v_max_f32_e32 v106, 1.0, v106
	v_mul_f32_e32 v115, 0x437f0000, v115
	v_rndne_f32_e32 v106, v106
	v_max_f32_e32 v115, 1.0, v115
	v_cvt_pk_u8_f32 v106, v106, 0, 0
	v_mul_f32_e32 v107, 0x437f0000, v107
	v_rndne_f32_e32 v115, v115
	v_max_f32_e32 v107, 1.0, v107
	v_cvt_pk_u8_f32 v106, v115, 1, v106
	v_mul_f32_e32 v115, 0xbfb8aa3b, v112
	v_mul_f32_e32 v119, 0x437f0000, v119
	v_rndne_f32_e32 v107, v107
	v_exp_f32_e32 v115, v115
	v_max_f32_e32 v119, 1.0, v119
	v_cvt_pk_u8_f32 v107, v107, 0, 0
	v_rndne_f32_e32 v119, v119
	v_cvt_pk_u8_f32 v107, v119, 1, v107
	v_mul_f32_e32 v119, 0xbfb8aa3b, v108
	v_exp_f32_e32 v119, v119
	v_add_f32_e32 v115, 1.0, v115
	v_rcp_f32_e32 v115, v115
	v_mul_f32_e32 v120, 0xbfb8aa3b, v113
	v_add_f32_e32 v119, 1.0, v119
	v_rcp_f32_e32 v119, v119
	v_exp_f32_e32 v120, v120
	v_mul_f32_e32 v115, 0x437f0000, v115
	v_max_f32_e32 v115, 1.0, v115
	v_rndne_f32_e32 v115, v115
	v_cvt_pk_u8_f32 v106, v115, 2, v106
	v_mul_f32_e32 v115, 0x437f0000, v119
	v_add_f32_e32 v119, 1.0, v120
	v_mul_f32_e32 v120, 0xbfb8aa3b, v109
	v_rcp_f32_e32 v119, v119
	v_exp_f32_e32 v120, v120
	v_max_f32_e32 v115, 1.0, v115
	v_rndne_f32_e32 v115, v115
	v_cvt_pk_u8_f32 v107, v115, 2, v107
	v_mul_f32_e32 v115, 0x437f0000, v119
	v_add_f32_e32 v119, 1.0, v120
	v_rcp_f32_e32 v119, v119
	v_max_f32_e32 v115, 1.0, v115
	v_rndne_f32_e32 v115, v115
	v_cvt_pk_u8_f32 v106, v115, 3, v106
	v_mul_f32_e32 v115, 0x437f0000, v119
	v_max_f32_e32 v115, 1.0, v115
	v_mov_b64_e32 v[120:121], s[30:31]
	v_rndne_f32_e32 v115, v115
	v_mad_i64_i32 v[120:121], s[0:1], v118, s55, v[120:121]
	v_cvt_pk_u8_f32 v107, v115, 3, v107
	v_lshl_add_u64 v[120:121], v[120:121], 0, v[140:141]
	s_mov_b64 s[0:1], 0
	v_mov_b32_e32 v246, v106
	v_mov_b32_e32 v247, v107

.LBB0_717:
	v_ffbh_u32_e32 v98, v155
	v_min_u32_e32 v100, 32, v98
	v_lshlrev_b64 v[98:99], v100, v[154:155]
	v_min_u32_e32 v98, 1, v98
	v_or_b32_e32 v98, v99, v98
	v_cvt_f32_u32_e32 v98, v98
	v_sub_u32_e32 v99, 32, v100
	v_or_b32_e32 v102, 32, v142
	s_mov_b64 s[0:1], -1
	v_ldexp_f32 v98, v98, v99
	v_mul_f32_e32 v98, 0x33800000, v98
	v_fmamk_f32 v98, v98, 0x3a800000, v210
	s_nop 1
	v_rsq_f32_e32 v98, v98
	s_nop 0
	s_nop 0
	v_pk_mul_f32 v[96:97], v[96:97], v[98:99] op_sel_hi:[1,0]
	v_pk_mul_f32 v[100:101], v[94:95], v[98:99] op_sel_hi:[1,0]
	v_pk_mul_f32 v[92:93], v[92:93], v[98:99] op_sel_hi:[1,0]
	v_pk_mul_f32 v[94:95], v[90:91], v[98:99] op_sel_hi:[1,0]
	s_and_b64 vcc, exec, s[42:43]
	s_cbranch_vccnz .LBB0_719
	v_mul_f32_e32 v90, 0xbfb8aa3b, v100
	v_exp_f32_e32 v90, v90
	v_mul_f32_e32 v99, 0xbfb8aa3b, v101
	v_exp_f32_e32 v99, v99
	v_mul_f32_e32 v91, 0xbfb8aa3b, v94
	v_exp_f32_e32 v91, v91
	v_mul_f32_e32 v103, 0xbfb8aa3b, v95
	v_add_f32_e32 v90, 1.0, v90
	v_exp_f32_e32 v103, v103
	v_rcp_f32_e32 v90, v90
	v_add_f32_e32 v99, 1.0, v99
	v_rcp_f32_e32 v99, v99
	v_add_f32_e32 v91, 1.0, v91
	v_rcp_f32_e32 v91, v91
	v_add_f32_e32 v103, 1.0, v103
	v_mul_f32_e32 v90, 0x437f0000, v90
	v_rcp_f32_e32 v103, v103
	v_max_f32_e32 v90, 1.0, v90
	v_mul_f32_e32 v99, 0x437f0000, v99
	v_rndne_f32_e32 v90, v90
	v_max_f32_e32 v99, 1.0, v99
	v_cvt_pk_u8_f32 v90, v90, 0, 0
	v_mul_f32_e32 v91, 0x437f0000, v91
	v_rndne_f32_e32 v99, v99
	v_max_f32_e32 v91, 1.0, v91
	v_cvt_pk_u8_f32 v90, v99, 1, v90
	v_mul_f32_e32 v99, 0xbfb8aa3b, v96
	v_mul_f32_e32 v103, 0x437f0000, v103
	v_rndne_f32_e32 v91, v91
	v_exp_f32_e32 v99, v99
	v_max_f32_e32 v103, 1.0, v103
	v_cvt_pk_u8_f32 v91, v91, 0, 0
	v_rndne_f32_e32 v103, v103
	v_cvt_pk_u8_f32 v91, v103, 1, v91
	v_mul_f32_e32 v103, 0xbfb8aa3b, v92
	v_exp_f32_e32 v103, v103
	v_add_f32_e32 v99, 1.0, v99
	v_rcp_f32_e32 v99, v99
	v_mul_f32_e32 v104, 0xbfb8aa3b, v97
	v_add_f32_e32 v103, 1.0, v103
	v_rcp_f32_e32 v103, v103
	v_exp_f32_e32 v104, v104
	v_mul_f32_e32 v99, 0x437f0000, v99
	v_max_f32_e32 v99, 1.0, v99
	v_rndne_f32_e32 v99, v99
	v_cvt_pk_u8_f32 v90, v99, 2, v90
	v_mul_f32_e32 v99, 0x437f0000, v103
	v_add_f32_e32 v103, 1.0, v104
	v_mul_f32_e32 v104, 0xbfb8aa3b, v93
	v_rcp_f32_e32 v103, v103
	v_exp_f32_e32 v104, v104
	v_max_f32_e32 v99, 1.0, v99
	v_rndne_f32_e32 v99, v99
	v_cvt_pk_u8_f32 v91, v99, 2, v91
	v_mul_f32_e32 v99, 0x437f0000, v103
	v_add_f32_e32 v103, 1.0, v104
	v_rcp_f32_e32 v103, v103
	v_max_f32_e32 v99, 1.0, v99
	v_rndne_f32_e32 v99, v99
	v_cvt_pk_u8_f32 v90, v99, 3, v90
	v_mul_f32_e32 v99, 0x437f0000, v103
	v_max_f32_e32 v99, 1.0, v99
	v_mov_b64_e32 v[104:105], s[30:31]
	v_rndne_f32_e32 v99, v99
	v_mad_i64_i32 v[104:105], s[0:1], v102, s55, v[104:105]
	v_cvt_pk_u8_f32 v91, v99, 3, v91
	v_lshl_add_u64 v[104:105], v[104:105], 0, v[140:141]
	s_mov_b64 s[0:1], 0
	v_mov_b32_e32 v246, v90
	v_mov_b32_e32 v247, v91

.LBB0_725:
	v_ffbh_u32_e32 v82, v153
	v_min_u32_e32 v84, 32, v82
	v_lshlrev_b64 v[82:83], v84, v[152:153]
	v_min_u32_e32 v82, 1, v82
	v_or_b32_e32 v82, v83, v82
	v_cvt_f32_u32_e32 v82, v82
	v_sub_u32_e32 v83, 32, v84
	v_or_b32_e32 v86, 48, v142
	s_mov_b64 s[0:1], -1
	v_ldexp_f32 v82, v82, v83
	v_mul_f32_e32 v82, 0x33800000, v82
	v_fmamk_f32 v82, v82, 0x3a800000, v210
	s_nop 1
	v_rsq_f32_e32 v82, v82
	s_nop 0
	s_nop 0
	v_pk_mul_f32 v[80:81], v[80:81], v[82:83] op_sel_hi:[1,0]
	v_pk_mul_f32 v[84:85], v[78:79], v[82:83] op_sel_hi:[1,0]
	v_pk_mul_f32 v[76:77], v[76:77], v[82:83] op_sel_hi:[1,0]
	v_pk_mul_f32 v[78:79], v[74:75], v[82:83] op_sel_hi:[1,0]
	s_and_b64 vcc, exec, s[42:43]
	s_cbranch_vccnz .LBB0_727
	v_mul_f32_e32 v74, 0xbfb8aa3b, v84
	v_exp_f32_e32 v74, v74
	v_mul_f32_e32 v83, 0xbfb8aa3b, v85
	v_exp_f32_e32 v83, v83
	v_mul_f32_e32 v75, 0xbfb8aa3b, v78
	v_exp_f32_e32 v75, v75
	v_mul_f32_e32 v87, 0xbfb8aa3b, v79
	v_add_f32_e32 v74, 1.0, v74
	v_exp_f32_e32 v87, v87
	v_rcp_f32_e32 v74, v74
	v_add_f32_e32 v83, 1.0, v83
	v_rcp_f32_e32 v83, v83
	v_add_f32_e32 v75, 1.0, v75
	v_rcp_f32_e32 v75, v75
	v_add_f32_e32 v87, 1.0, v87
	v_mul_f32_e32 v74, 0x437f0000, v74
	v_rcp_f32_e32 v87, v87
	v_max_f32_e32 v74, 1.0, v74
	v_mul_f32_e32 v83, 0x437f0000, v83
	v_rndne_f32_e32 v74, v74
	v_max_f32_e32 v83, 1.0, v83
	v_cvt_pk_u8_f32 v74, v74, 0, 0
	v_mul_f32_e32 v75, 0x437f0000, v75
	v_rndne_f32_e32 v83, v83
	v_max_f32_e32 v75, 1.0, v75
	v_cvt_pk_u8_f32 v74, v83, 1, v74
	v_mul_f32_e32 v83, 0xbfb8aa3b, v80
	v_mul_f32_e32 v87, 0x437f0000, v87
	v_rndne_f32_e32 v75, v75
	v_exp_f32_e32 v83, v83
	v_max_f32_e32 v87, 1.0, v87
	v_cvt_pk_u8_f32 v75, v75, 0, 0
	v_rndne_f32_e32 v87, v87
	v_cvt_pk_u8_f32 v75, v87, 1, v75
	v_mul_f32_e32 v87, 0xbfb8aa3b, v76
	v_exp_f32_e32 v87, v87
	v_add_f32_e32 v83, 1.0, v83
	v_rcp_f32_e32 v83, v83
	v_mul_f32_e32 v88, 0xbfb8aa3b, v81
	v_add_f32_e32 v87, 1.0, v87
	v_rcp_f32_e32 v87, v87
	v_exp_f32_e32 v88, v88
	v_mul_f32_e32 v83, 0x437f0000, v83
	v_max_f32_e32 v83, 1.0, v83
	v_rndne_f32_e32 v83, v83
	v_cvt_pk_u8_f32 v74, v83, 2, v74
	v_mul_f32_e32 v83, 0x437f0000, v87
	v_add_f32_e32 v87, 1.0, v88
	v_mul_f32_e32 v88, 0xbfb8aa3b, v77
	v_rcp_f32_e32 v87, v87
	v_exp_f32_e32 v88, v88
	v_max_f32_e32 v83, 1.0, v83
	v_rndne_f32_e32 v83, v83
	v_cvt_pk_u8_f32 v75, v83, 2, v75
	v_mul_f32_e32 v83, 0x437f0000, v87
	v_add_f32_e32 v87, 1.0, v88
	v_rcp_f32_e32 v87, v87
	v_max_f32_e32 v83, 1.0, v83
	v_rndne_f32_e32 v83, v83
	v_cvt_pk_u8_f32 v74, v83, 3, v74
	v_mul_f32_e32 v83, 0x437f0000, v87
	v_max_f32_e32 v83, 1.0, v83
	v_mov_b64_e32 v[88:89], s[30:31]
	v_rndne_f32_e32 v83, v83
	v_mad_i64_i32 v[88:89], s[0:1], v86, s55, v[88:89]
	v_cvt_pk_u8_f32 v75, v83, 3, v75
	v_lshl_add_u64 v[88:89], v[88:89], 0, v[140:141]
	s_mov_b64 s[0:1], 0
	v_mov_b32_e32 v246, v74
	v_mov_b32_e32 v247, v75

.LBB0_733:
	v_ffbh_u32_e32 v66, v151
	v_min_u32_e32 v68, 32, v66
	v_lshlrev_b64 v[66:67], v68, v[150:151]
	v_min_u32_e32 v66, 1, v66
	v_or_b32_e32 v66, v67, v66
	v_cvt_f32_u32_e32 v66, v66
	v_sub_u32_e32 v67, 32, v68
	v_add_u32_e32 v70, 0x80, v142
	s_mov_b64 s[0:1], -1
	v_ldexp_f32 v66, v66, v67
	v_mul_f32_e32 v66, 0x33800000, v66
	v_fmamk_f32 v66, v66, 0x3a800000, v210
	s_nop 1
	v_rsq_f32_e32 v66, v66
	s_nop 0
	s_nop 0
	v_pk_mul_f32 v[64:65], v[64:65], v[66:67] op_sel_hi:[1,0]
	v_pk_mul_f32 v[68:69], v[62:63], v[66:67] op_sel_hi:[1,0]
	v_pk_mul_f32 v[60:61], v[60:61], v[66:67] op_sel_hi:[1,0]
	v_pk_mul_f32 v[62:63], v[58:59], v[66:67] op_sel_hi:[1,0]
	s_and_b64 vcc, exec, s[42:43]
	s_cbranch_vccnz .LBB0_735
	v_mul_f32_e32 v58, 0xbfb8aa3b, v68
	v_exp_f32_e32 v58, v58
	v_mul_f32_e32 v67, 0xbfb8aa3b, v69
	v_exp_f32_e32 v67, v67
	v_mul_f32_e32 v59, 0xbfb8aa3b, v62
	v_exp_f32_e32 v59, v59
	v_mul_f32_e32 v71, 0xbfb8aa3b, v63
	v_add_f32_e32 v58, 1.0, v58
	v_exp_f32_e32 v71, v71
	v_rcp_f32_e32 v58, v58
	v_add_f32_e32 v67, 1.0, v67
	v_rcp_f32_e32 v67, v67
	v_add_f32_e32 v59, 1.0, v59
	v_rcp_f32_e32 v59, v59
	v_add_f32_e32 v71, 1.0, v71
	v_mul_f32_e32 v58, 0x437f0000, v58
	v_rcp_f32_e32 v71, v71
	v_max_f32_e32 v58, 1.0, v58
	v_mul_f32_e32 v67, 0x437f0000, v67
	v_rndne_f32_e32 v58, v58
	v_max_f32_e32 v67, 1.0, v67
	v_cvt_pk_u8_f32 v58, v58, 0, 0
	v_mul_f32_e32 v59, 0x437f0000, v59
	v_rndne_f32_e32 v67, v67
	v_max_f32_e32 v59, 1.0, v59
	v_cvt_pk_u8_f32 v58, v67, 1, v58
	v_mul_f32_e32 v67, 0xbfb8aa3b, v64
	v_mul_f32_e32 v71, 0x437f0000, v71
	v_rndne_f32_e32 v59, v59
	v_exp_f32_e32 v67, v67
	v_max_f32_e32 v71, 1.0, v71
	v_cvt_pk_u8_f32 v59, v59, 0, 0
	v_rndne_f32_e32 v71, v71
	v_cvt_pk_u8_f32 v59, v71, 1, v59
	v_mul_f32_e32 v71, 0xbfb8aa3b, v60
	v_exp_f32_e32 v71, v71
	v_add_f32_e32 v67, 1.0, v67
	v_rcp_f32_e32 v67, v67
	v_mul_f32_e32 v72, 0xbfb8aa3b, v65
	v_add_f32_e32 v71, 1.0, v71
	v_rcp_f32_e32 v71, v71
	v_exp_f32_e32 v72, v72
	v_mul_f32_e32 v67, 0x437f0000, v67
	v_max_f32_e32 v67, 1.0, v67
	v_rndne_f32_e32 v67, v67
	v_cvt_pk_u8_f32 v58, v67, 2, v58
	v_mul_f32_e32 v67, 0x437f0000, v71
	v_add_f32_e32 v71, 1.0, v72
	v_mul_f32_e32 v72, 0xbfb8aa3b, v61
	v_rcp_f32_e32 v71, v71
	v_exp_f32_e32 v72, v72
	v_max_f32_e32 v67, 1.0, v67
	v_rndne_f32_e32 v67, v67
	v_cvt_pk_u8_f32 v59, v67, 2, v59
	v_mul_f32_e32 v67, 0x437f0000, v71
	v_add_f32_e32 v71, 1.0, v72
	v_rcp_f32_e32 v71, v71
	v_max_f32_e32 v67, 1.0, v67
	v_rndne_f32_e32 v67, v67
	v_cvt_pk_u8_f32 v58, v67, 3, v58
	v_mul_f32_e32 v67, 0x437f0000, v71
	v_max_f32_e32 v67, 1.0, v67
	v_mov_b64_e32 v[72:73], s[30:31]
	v_rndne_f32_e32 v67, v67
	v_mad_i64_i32 v[72:73], s[0:1], v70, s55, v[72:73]
	v_cvt_pk_u8_f32 v59, v67, 3, v59
	v_lshl_add_u64 v[72:73], v[72:73], 0, v[140:141]
	s_mov_b64 s[0:1], 0
	v_mov_b32_e32 v246, v58
	v_mov_b32_e32 v247, v59

.LBB0_741:
	v_ffbh_u32_e32 v50, v149
	v_min_u32_e32 v52, 32, v50
	v_lshlrev_b64 v[50:51], v52, v[148:149]
	v_min_u32_e32 v50, 1, v50
	v_or_b32_e32 v50, v51, v50
	v_cvt_f32_u32_e32 v50, v50
	v_sub_u32_e32 v51, 32, v52
	v_add_u32_e32 v54, 0x90, v142
	s_mov_b64 s[0:1], -1
	v_ldexp_f32 v50, v50, v51
	v_mul_f32_e32 v50, 0x33800000, v50
	v_fmamk_f32 v50, v50, 0x3a800000, v210
	s_nop 1
	v_rsq_f32_e32 v50, v50
	s_nop 0
	s_nop 0
	v_pk_mul_f32 v[48:49], v[48:49], v[50:51] op_sel_hi:[1,0]
	v_pk_mul_f32 v[52:53], v[46:47], v[50:51] op_sel_hi:[1,0]
	v_pk_mul_f32 v[44:45], v[44:45], v[50:51] op_sel_hi:[1,0]
	v_pk_mul_f32 v[46:47], v[42:43], v[50:51] op_sel_hi:[1,0]
	s_and_b64 vcc, exec, s[42:43]
	s_cbranch_vccnz .LBB0_743
	v_mul_f32_e32 v42, 0xbfb8aa3b, v52
	v_exp_f32_e32 v42, v42
	v_mul_f32_e32 v51, 0xbfb8aa3b, v53
	v_exp_f32_e32 v51, v51
	v_mul_f32_e32 v43, 0xbfb8aa3b, v46
	v_exp_f32_e32 v43, v43
	v_mul_f32_e32 v55, 0xbfb8aa3b, v47
	v_add_f32_e32 v42, 1.0, v42
	v_exp_f32_e32 v55, v55
	v_rcp_f32_e32 v42, v42
	v_add_f32_e32 v51, 1.0, v51
	v_rcp_f32_e32 v51, v51
	v_add_f32_e32 v43, 1.0, v43
	v_rcp_f32_e32 v43, v43
	v_add_f32_e32 v55, 1.0, v55
	v_mul_f32_e32 v42, 0x437f0000, v42
	v_rcp_f32_e32 v55, v55
	v_max_f32_e32 v42, 1.0, v42
	v_mul_f32_e32 v51, 0x437f0000, v51
	v_rndne_f32_e32 v42, v42
	v_max_f32_e32 v51, 1.0, v51
	v_cvt_pk_u8_f32 v42, v42, 0, 0
	v_mul_f32_e32 v43, 0x437f0000, v43
	v_rndne_f32_e32 v51, v51
	v_max_f32_e32 v43, 1.0, v43
	v_cvt_pk_u8_f32 v42, v51, 1, v42
	v_mul_f32_e32 v51, 0xbfb8aa3b, v48
	v_mul_f32_e32 v55, 0x437f0000, v55
	v_rndne_f32_e32 v43, v43
	v_exp_f32_e32 v51, v51
	v_max_f32_e32 v55, 1.0, v55
	v_cvt_pk_u8_f32 v43, v43, 0, 0
	v_rndne_f32_e32 v55, v55
	v_cvt_pk_u8_f32 v43, v55, 1, v43
	v_mul_f32_e32 v55, 0xbfb8aa3b, v44
	v_exp_f32_e32 v55, v55
	v_add_f32_e32 v51, 1.0, v51
	v_rcp_f32_e32 v51, v51
	v_mul_f32_e32 v56, 0xbfb8aa3b, v49
	v_add_f32_e32 v55, 1.0, v55
	v_rcp_f32_e32 v55, v55
	v_exp_f32_e32 v56, v56
	v_mul_f32_e32 v51, 0x437f0000, v51
	v_max_f32_e32 v51, 1.0, v51
	v_rndne_f32_e32 v51, v51
	v_cvt_pk_u8_f32 v42, v51, 2, v42
	v_mul_f32_e32 v51, 0x437f0000, v55
	v_add_f32_e32 v55, 1.0, v56
	v_mul_f32_e32 v56, 0xbfb8aa3b, v45
	v_rcp_f32_e32 v55, v55
	v_exp_f32_e32 v56, v56
	v_max_f32_e32 v51, 1.0, v51
	v_rndne_f32_e32 v51, v51
	v_cvt_pk_u8_f32 v43, v51, 2, v43
	v_mul_f32_e32 v51, 0x437f0000, v55
	v_add_f32_e32 v55, 1.0, v56
	v_rcp_f32_e32 v55, v55
	v_max_f32_e32 v51, 1.0, v51
	v_rndne_f32_e32 v51, v51
	v_cvt_pk_u8_f32 v42, v51, 3, v42
	v_mul_f32_e32 v51, 0x437f0000, v55
	v_max_f32_e32 v51, 1.0, v51
	v_mov_b64_e32 v[56:57], s[30:31]
	v_rndne_f32_e32 v51, v51
	v_mad_i64_i32 v[56:57], s[0:1], v54, s55, v[56:57]
	v_cvt_pk_u8_f32 v43, v51, 3, v43
	v_lshl_add_u64 v[56:57], v[56:57], 0, v[140:141]
	s_mov_b64 s[0:1], 0
	v_mov_b32_e32 v246, v42
	v_mov_b32_e32 v247, v43

.LBB0_749:
	v_ffbh_u32_e32 v34, v147
	v_min_u32_e32 v36, 32, v34
	v_lshlrev_b64 v[34:35], v36, v[146:147]
	v_min_u32_e32 v34, 1, v34
	v_or_b32_e32 v34, v35, v34
	v_cvt_f32_u32_e32 v34, v34
	v_sub_u32_e32 v35, 32, v36
	v_add_u32_e32 v38, 0xa0, v142
	s_mov_b64 s[0:1], -1
	v_ldexp_f32 v34, v34, v35
	v_mul_f32_e32 v34, 0x33800000, v34
	v_fmamk_f32 v34, v34, 0x3a800000, v210
	s_nop 1
	v_rsq_f32_e32 v34, v34
	s_nop 0
	s_nop 0
	v_pk_mul_f32 v[32:33], v[32:33], v[34:35] op_sel_hi:[1,0]
	v_pk_mul_f32 v[36:37], v[30:31], v[34:35] op_sel_hi:[1,0]
	v_pk_mul_f32 v[28:29], v[28:29], v[34:35] op_sel_hi:[1,0]
	v_pk_mul_f32 v[30:31], v[26:27], v[34:35] op_sel_hi:[1,0]
	s_and_b64 vcc, exec, s[42:43]
	s_cbranch_vccnz .LBB0_751
	v_mul_f32_e32 v26, 0xbfb8aa3b, v36
	v_exp_f32_e32 v26, v26
	v_mul_f32_e32 v35, 0xbfb8aa3b, v37
	v_exp_f32_e32 v35, v35
	v_mul_f32_e32 v27, 0xbfb8aa3b, v30
	v_exp_f32_e32 v27, v27
	v_mul_f32_e32 v39, 0xbfb8aa3b, v31
	v_add_f32_e32 v26, 1.0, v26
	v_exp_f32_e32 v39, v39
	v_rcp_f32_e32 v26, v26
	v_add_f32_e32 v35, 1.0, v35
	v_rcp_f32_e32 v35, v35
	v_add_f32_e32 v27, 1.0, v27
	v_rcp_f32_e32 v27, v27
	v_add_f32_e32 v39, 1.0, v39
	v_mul_f32_e32 v26, 0x437f0000, v26
	v_rcp_f32_e32 v39, v39
	v_max_f32_e32 v26, 1.0, v26
	v_mul_f32_e32 v35, 0x437f0000, v35
	v_rndne_f32_e32 v26, v26
	v_max_f32_e32 v35, 1.0, v35
	v_cvt_pk_u8_f32 v26, v26, 0, 0
	v_mul_f32_e32 v27, 0x437f0000, v27
	v_rndne_f32_e32 v35, v35
	v_max_f32_e32 v27, 1.0, v27
	v_cvt_pk_u8_f32 v26, v35, 1, v26
	v_mul_f32_e32 v35, 0xbfb8aa3b, v32
	v_mul_f32_e32 v39, 0x437f0000, v39
	v_rndne_f32_e32 v27, v27
	v_exp_f32_e32 v35, v35
	v_max_f32_e32 v39, 1.0, v39
	v_cvt_pk_u8_f32 v27, v27, 0, 0
	v_rndne_f32_e32 v39, v39
	v_cvt_pk_u8_f32 v27, v39, 1, v27
	v_mul_f32_e32 v39, 0xbfb8aa3b, v28
	v_exp_f32_e32 v39, v39
	v_add_f32_e32 v35, 1.0, v35
	v_rcp_f32_e32 v35, v35
	v_mul_f32_e32 v40, 0xbfb8aa3b, v33
	v_add_f32_e32 v39, 1.0, v39
	v_rcp_f32_e32 v39, v39
	v_exp_f32_e32 v40, v40
	v_mul_f32_e32 v35, 0x437f0000, v35
	v_max_f32_e32 v35, 1.0, v35
	v_rndne_f32_e32 v35, v35
	v_cvt_pk_u8_f32 v26, v35, 2, v26
	v_mul_f32_e32 v35, 0x437f0000, v39
	v_add_f32_e32 v39, 1.0, v40
	v_mul_f32_e32 v40, 0xbfb8aa3b, v29
	v_rcp_f32_e32 v39, v39
	v_exp_f32_e32 v40, v40
	v_max_f32_e32 v35, 1.0, v35
	v_rndne_f32_e32 v35, v35
	v_cvt_pk_u8_f32 v27, v35, 2, v27
	v_mul_f32_e32 v35, 0x437f0000, v39
	v_add_f32_e32 v39, 1.0, v40
	v_rcp_f32_e32 v39, v39
	v_max_f32_e32 v35, 1.0, v35
	v_rndne_f32_e32 v35, v35
	v_cvt_pk_u8_f32 v26, v35, 3, v26
	v_mul_f32_e32 v35, 0x437f0000, v39
	v_max_f32_e32 v35, 1.0, v35
	v_mov_b64_e32 v[40:41], s[30:31]
	v_rndne_f32_e32 v35, v35
	v_mad_i64_i32 v[40:41], s[0:1], v38, s55, v[40:41]
	v_cvt_pk_u8_f32 v27, v35, 3, v27
	v_lshl_add_u64 v[40:41], v[40:41], 0, v[140:141]
	s_mov_b64 s[0:1], 0
	v_mov_b32_e32 v246, v26
	v_mov_b32_e32 v247, v27

.LBB0_757:
	v_ffbh_u32_e32 v18, v145
	v_min_u32_e32 v20, 32, v18
	v_lshlrev_b64 v[18:19], v20, v[144:145]
	v_min_u32_e32 v18, 1, v18
	v_or_b32_e32 v18, v19, v18
	v_cvt_f32_u32_e32 v18, v18
	v_sub_u32_e32 v19, 32, v20
	v_add_u32_e32 v22, 0xb0, v142
	s_mov_b64 s[0:1], -1
	v_ldexp_f32 v18, v18, v19
	v_mul_f32_e32 v18, 0x33800000, v18
	v_fmamk_f32 v18, v18, 0x3a800000, v210
	s_nop 1
	v_rsq_f32_e32 v18, v18
	s_nop 0
	s_nop 0
	v_pk_mul_f32 v[16:17], v[16:17], v[18:19] op_sel_hi:[1,0]
	v_pk_mul_f32 v[20:21], v[14:15], v[18:19] op_sel_hi:[1,0]
	v_pk_mul_f32 v[12:13], v[12:13], v[18:19] op_sel_hi:[1,0]
	v_pk_mul_f32 v[14:15], v[10:11], v[18:19] op_sel_hi:[1,0]
	s_and_b64 vcc, exec, s[42:43]
	s_cbranch_vccnz .LBB0_759
	v_mul_f32_e32 v10, 0xbfb8aa3b, v20
	v_exp_f32_e32 v10, v10
	v_mul_f32_e32 v19, 0xbfb8aa3b, v21
	v_exp_f32_e32 v19, v19
	v_mul_f32_e32 v11, 0xbfb8aa3b, v14
	v_exp_f32_e32 v11, v11
	v_mul_f32_e32 v23, 0xbfb8aa3b, v15
	v_add_f32_e32 v10, 1.0, v10
	v_exp_f32_e32 v23, v23
	v_rcp_f32_e32 v10, v10
	v_add_f32_e32 v19, 1.0, v19
	v_rcp_f32_e32 v19, v19
	v_add_f32_e32 v11, 1.0, v11
	v_rcp_f32_e32 v11, v11
	v_add_f32_e32 v23, 1.0, v23
	v_mul_f32_e32 v10, 0x437f0000, v10
	v_rcp_f32_e32 v23, v23
	v_max_f32_e32 v10, 1.0, v10
	v_mul_f32_e32 v19, 0x437f0000, v19
	v_rndne_f32_e32 v10, v10
	v_max_f32_e32 v19, 1.0, v19
	v_cvt_pk_u8_f32 v10, v10, 0, 0
	v_mul_f32_e32 v11, 0x437f0000, v11
	v_rndne_f32_e32 v19, v19
	v_max_f32_e32 v11, 1.0, v11
	v_cvt_pk_u8_f32 v10, v19, 1, v10
	v_mul_f32_e32 v19, 0xbfb8aa3b, v16
	v_mul_f32_e32 v23, 0x437f0000, v23
	v_rndne_f32_e32 v11, v11
	v_exp_f32_e32 v19, v19
	v_max_f32_e32 v23, 1.0, v23
	v_cvt_pk_u8_f32 v11, v11, 0, 0
	v_rndne_f32_e32 v23, v23
	v_cvt_pk_u8_f32 v11, v23, 1, v11
	v_mul_f32_e32 v23, 0xbfb8aa3b, v12
	v_exp_f32_e32 v23, v23
	v_add_f32_e32 v19, 1.0, v19
	v_rcp_f32_e32 v19, v19
	v_mul_f32_e32 v24, 0xbfb8aa3b, v17
	v_add_f32_e32 v23, 1.0, v23
	v_rcp_f32_e32 v23, v23
	v_exp_f32_e32 v24, v24
	v_mul_f32_e32 v19, 0x437f0000, v19
	v_max_f32_e32 v19, 1.0, v19
	v_rndne_f32_e32 v19, v19
	v_cvt_pk_u8_f32 v10, v19, 2, v10
	v_mul_f32_e32 v19, 0x437f0000, v23
	v_add_f32_e32 v23, 1.0, v24
	v_mul_f32_e32 v24, 0xbfb8aa3b, v13
	v_rcp_f32_e32 v23, v23
	v_exp_f32_e32 v24, v24
	v_max_f32_e32 v19, 1.0, v19
	v_rndne_f32_e32 v19, v19
	v_cvt_pk_u8_f32 v11, v19, 2, v11
	v_mul_f32_e32 v19, 0x437f0000, v23
	v_add_f32_e32 v23, 1.0, v24
	v_rcp_f32_e32 v23, v23
	v_max_f32_e32 v19, 1.0, v19
	v_rndne_f32_e32 v19, v19
	v_cvt_pk_u8_f32 v10, v19, 3, v10
	v_mul_f32_e32 v19, 0x437f0000, v23
	v_max_f32_e32 v19, 1.0, v19
	v_mov_b64_e32 v[24:25], s[30:31]
	v_rndne_f32_e32 v19, v19
	v_mad_i64_i32 v[24:25], s[0:1], v22, s55, v[24:25]
	v_cvt_pk_u8_f32 v11, v19, 3, v11
	v_lshl_add_u64 v[24:25], v[24:25], 0, v[140:141]
	s_mov_b64 s[0:1], 0
	v_mov_b32_e32 v246, v10
	v_mov_b32_e32 v247, v11
